# v022 + Swiglu epilogue: row broadcasts interleaved per group with counted lgkmcnt at each group's first use (instead of one lgkmcnt(0) after all 16)
# speedup vs baseline: 1.0067x; 1.0067x over previous
; __device__ __forceinline__ unsigned pk_bf16(float lo, float hi) { f32x2 v = {lo, hi}; bf16x2_t b = __builtin_convertvector(v, bf16x2_t); return __builtin_bit_cast(unsigned, b); }
; __device__ __forceinline__ float fast_exp2(float x) { return __builtin_amdgcn_exp2f(x); }
; __device__ __forceinline__ float fast_rcp(float x) { return __builtin_amdgcn_rcpf(x); }
;     __device__ __forceinline__ void operator()(const f32x4 (&acc)[2][2][4][2], const Unit& u, int wr, int wc, int fr, int fq, float rp0, float rp1, const f32x4& raw0, const f32x4& raw1, float& rn0, float& rn1) const {
;     ...
;         for (int k = 0; k < 8; ++k) rs[k] = __shfl((k >> 2) ? rp1 : rp0, fr + 16 * (k & 3));
; #pragma unroll
;         for (int ai = 0; ai < 2; ++ai)
; #pragma unroll
;             for (int m = 0; m < 4; ++m) {
;                 const int row = row0 + ai * HALF + m * 16; const float r = rs[ai * 4 + m];
;                 const float c1 = -1.4426950408889634f * r, r2 = r * r;
;                 const f32x4 ga = acc[ai][0][m][0], gb = acc[ai][0][m][1];
;                 const f32x4 ta = ga * c1, tb = gb * c1;
;                 f32x4 ea, eb;
; #pragma unroll
;                 for (int j = 0; j < 4; ++j) { ea[j] = fast_exp2(ta[j]); eb[j] = fast_exp2(tb[j]); }
;                 const f32x4 da = ea + 1.f, db = eb + 1.f;
;                 f32x4 qa, qb;
; #pragma unroll
;                 for (int j = 0; j < 4; ++j) { qa[j] = fast_rcp(da[j]); qb[j] = fast_rcp(db[j]); }
;                 const f32x4 oa = ((ga * acc[ai][1][m][0]) * r2) * qa, ob = ((gb * acc[ai][1][m][1]) * r2) * qb;
;                 u32x4 w;
;                 w.x = pk_bf16(oa[0], oa[1]); w.y = pk_bf16(oa[2], oa[3]); w.z = pk_bf16(ob[0], ob[1]); w.w = pk_bf16(ob[2], ob[3]);
;                 if (ai == 0 && m == 0) rstd_finish(raw0, raw1, rn0, rn1);
;                 *(u32x4*)(O + (size_t)row * FF + col0) = w;
.LBB0_322:
	s_andn2_b64 vcc, exec, s[4:5]
	s_mov_b64 s[4:5], -1
	v_and_or_b32 v157, v197, 64, v154
	v_lshlrev_b32_e32 v157, 2, v157
	ds_bpermute_b32 v162, v157, v144
	ds_bpermute_b32 v200, v157, v252
	ds_bpermute_b32 v163, v157, v144 offset:64
	ds_bpermute_b32 v202, v157, v252 offset:64
	ds_bpermute_b32 v164, v157, v144 offset:128
	ds_bpermute_b32 v204, v157, v252 offset:128
	ds_bpermute_b32 v165, v157, v144 offset:192
	ds_bpermute_b32 v206, v157, v252 offset:192
	ds_bpermute_b32 v166, v157, v145
	ds_bpermute_b32 v220, v157, v253
	ds_bpermute_b32 v167, v157, v145 offset:64
	ds_bpermute_b32 v222, v157, v253 offset:64
	ds_bpermute_b32 v168, v157, v145 offset:128
	ds_bpermute_b32 v224, v157, v253 offset:128
	ds_bpermute_b32 v169, v157, v145 offset:192
	ds_bpermute_b32 v226, v157, v253 offset:192
	v_lshl_add_u32 v153, s6, 8, v155
	v_lshl_or_b32 v160, s7, 7, v151
	v_mul_u32_u24_e32 v161, 0x1600, v153
	v_lshl_add_u32 v161, v160, 1, v161
	s_waitcnt lgkmcnt(14)
	v_mul_f32_e32 v228, 0xbfb8aa3b, v162
	v_pk_mul_f32 v[126:127], v[118:119], v[126:127]
	v_pk_mul_f32 v[128:129], v[120:121], v[128:129]
	v_pk_mul_f32 v[122:123], v[114:115], v[122:123]
	v_pk_mul_f32 v[124:125], v[116:117], v[124:125]
	v_pk_mul_f32 v[118:119], v[118:119], v[228:229] op_sel_hi:[1,0]
	v_pk_mul_f32 v[120:121], v[120:121], v[228:229] op_sel_hi:[1,0]
	v_pk_mul_f32 v[114:115], v[114:115], v[228:229] op_sel_hi:[1,0]
	v_pk_mul_f32 v[116:117], v[116:117], v[228:229] op_sel_hi:[1,0]
	v_exp_f32_e32 v118, v118
	v_exp_f32_e32 v119, v119
	v_exp_f32_e32 v120, v120
	v_exp_f32_e32 v121, v121
	v_exp_f32_e32 v114, v114
	v_exp_f32_e32 v115, v115
	v_exp_f32_e32 v116, v116
	v_exp_f32_e32 v117, v117
	v_pk_fma_f32 v[118:119], v[118:119], v[200:201], v[200:201] op_sel_hi:[1,0,0]
	v_pk_fma_f32 v[120:121], v[120:121], v[200:201], v[200:201] op_sel_hi:[1,0,0]
	v_pk_fma_f32 v[114:115], v[114:115], v[200:201], v[200:201] op_sel_hi:[1,0,0]
	v_pk_fma_f32 v[116:117], v[116:117], v[200:201], v[200:201] op_sel_hi:[1,0,0]
	v_rcp_f32_e32 v118, v118
	v_rcp_f32_e32 v119, v119
	v_rcp_f32_e32 v120, v120
	v_rcp_f32_e32 v121, v121
	v_rcp_f32_e32 v114, v114
	v_rcp_f32_e32 v115, v115
	v_rcp_f32_e32 v116, v116
	v_rcp_f32_e32 v117, v117
	v_pk_mul_f32 v[126:127], v[126:127], v[118:119]
	v_pk_mul_f32 v[128:129], v[128:129], v[120:121]
	v_pk_mul_f32 v[122:123], v[122:123], v[114:115]
	v_pk_mul_f32 v[124:125], v[124:125], v[116:117]
	v_cvt_pk_bf16_f32 v118, v126, v127
	v_cvt_pk_bf16_f32 v119, v128, v129
	v_cvt_pk_bf16_f32 v120, v122, v123
	v_cvt_pk_bf16_f32 v121, v124, v125
	global_store_dwordx4 v161, v[118:121], s[24:25]
	s_waitcnt lgkmcnt(12)
	v_mul_f32_e32 v228, 0xbfb8aa3b, v163
	v_pk_mul_f32 v[110:111], v[102:103], v[110:111]
	v_pk_mul_f32 v[112:113], v[104:105], v[112:113]
	v_pk_mul_f32 v[106:107], v[98:99], v[106:107]
	v_pk_mul_f32 v[108:109], v[100:101], v[108:109]
	v_pk_mul_f32 v[102:103], v[102:103], v[228:229] op_sel_hi:[1,0]
	v_pk_mul_f32 v[104:105], v[104:105], v[228:229] op_sel_hi:[1,0]
	v_pk_mul_f32 v[98:99], v[98:99], v[228:229] op_sel_hi:[1,0]
	v_pk_mul_f32 v[100:101], v[100:101], v[228:229] op_sel_hi:[1,0]
	v_exp_f32_e32 v102, v102
	v_exp_f32_e32 v103, v103
	v_exp_f32_e32 v104, v104
	v_exp_f32_e32 v105, v105
	v_exp_f32_e32 v98, v98
	v_exp_f32_e32 v99, v99
	v_exp_f32_e32 v100, v100
	v_exp_f32_e32 v101, v101
	v_pk_fma_f32 v[102:103], v[102:103], v[202:203], v[202:203] op_sel_hi:[1,0,0]
	v_pk_fma_f32 v[104:105], v[104:105], v[202:203], v[202:203] op_sel_hi:[1,0,0]
	v_pk_fma_f32 v[98:99], v[98:99], v[202:203], v[202:203] op_sel_hi:[1,0,0]
	v_pk_fma_f32 v[100:101], v[100:101], v[202:203], v[202:203] op_sel_hi:[1,0,0]
	v_rcp_f32_e32 v102, v102
	v_rcp_f32_e32 v103, v103
	v_rcp_f32_e32 v104, v104
	v_rcp_f32_e32 v105, v105
	v_rcp_f32_e32 v98, v98
	v_rcp_f32_e32 v99, v99
	v_rcp_f32_e32 v100, v100
	v_rcp_f32_e32 v101, v101
	v_pk_mul_f32 v[110:111], v[110:111], v[102:103]
	v_pk_mul_f32 v[112:113], v[112:113], v[104:105]
	v_pk_mul_f32 v[106:107], v[106:107], v[98:99]
	v_pk_mul_f32 v[108:109], v[108:109], v[100:101]
	v_cvt_pk_bf16_f32 v102, v110, v111
	v_cvt_pk_bf16_f32 v103, v112, v113
	v_cvt_pk_bf16_f32 v104, v106, v107
	v_cvt_pk_bf16_f32 v105, v108, v109
	v_add_u32_e32 v170, 0x16000, v161
	global_store_dwordx4 v170, v[102:105], s[24:25]
	s_waitcnt lgkmcnt(10)
	v_mul_f32_e32 v228, 0xbfb8aa3b, v164
	v_pk_mul_f32 v[94:95], v[86:87], v[94:95]
	v_pk_mul_f32 v[96:97], v[88:89], v[96:97]
	v_pk_mul_f32 v[90:91], v[82:83], v[90:91]
	v_pk_mul_f32 v[92:93], v[84:85], v[92:93]
	v_pk_mul_f32 v[86:87], v[86:87], v[228:229] op_sel_hi:[1,0]
	v_pk_mul_f32 v[88:89], v[88:89], v[228:229] op_sel_hi:[1,0]
	v_pk_mul_f32 v[82:83], v[82:83], v[228:229] op_sel_hi:[1,0]
	v_pk_mul_f32 v[84:85], v[84:85], v[228:229] op_sel_hi:[1,0]
	v_exp_f32_e32 v86, v86
	v_exp_f32_e32 v87, v87
	v_exp_f32_e32 v88, v88
	v_exp_f32_e32 v89, v89
	v_exp_f32_e32 v82, v82
	v_exp_f32_e32 v83, v83
	v_exp_f32_e32 v84, v84
	v_exp_f32_e32 v85, v85
	v_pk_fma_f32 v[86:87], v[86:87], v[204:205], v[204:205] op_sel_hi:[1,0,0]
	v_pk_fma_f32 v[88:89], v[88:89], v[204:205], v[204:205] op_sel_hi:[1,0,0]
	v_pk_fma_f32 v[82:83], v[82:83], v[204:205], v[204:205] op_sel_hi:[1,0,0]
	v_pk_fma_f32 v[84:85], v[84:85], v[204:205], v[204:205] op_sel_hi:[1,0,0]
	v_rcp_f32_e32 v86, v86
	v_rcp_f32_e32 v87, v87
	v_rcp_f32_e32 v88, v88
	v_rcp_f32_e32 v89, v89
	v_rcp_f32_e32 v82, v82
	v_rcp_f32_e32 v83, v83
	v_rcp_f32_e32 v84, v84
	v_rcp_f32_e32 v85, v85
	v_pk_mul_f32 v[94:95], v[94:95], v[86:87]
	v_pk_mul_f32 v[96:97], v[96:97], v[88:89]
	v_pk_mul_f32 v[90:91], v[90:91], v[82:83]
	v_pk_mul_f32 v[92:93], v[92:93], v[84:85]
	v_cvt_pk_bf16_f32 v86, v94, v95
	v_cvt_pk_bf16_f32 v87, v96, v97
	v_cvt_pk_bf16_f32 v88, v90, v91
	v_cvt_pk_bf16_f32 v89, v92, v93
	v_add_u32_e32 v170, 0x2c000, v161
	global_store_dwordx4 v170, v[86:89], s[24:25]
	s_waitcnt lgkmcnt(8)
; __device__ __forceinline__ unsigned pk_bf16(float lo, float hi) { f32x2 v = {lo, hi}; bf16x2_t b = __builtin_convertvector(v, bf16x2_t); return __builtin_bit_cast(unsigned, b); }
; __device__ __forceinline__ float fast_exp2(float x) { return __builtin_amdgcn_exp2f(x); }
; __device__ __forceinline__ float fast_rcp(float x) { return __builtin_amdgcn_rcpf(x); }
;     __device__ __forceinline__ void operator()(const f32x4 (&acc)[2][2][4][2], const Unit& u, int wr, int wc, int fr, int fq, float rp0, float rp1, const f32x4& raw0, const f32x4& raw1, float& rn0, float& rn1) const {
;     ...
;                 const int row = row0 + ai * HALF + m * 16; const float r = rs[ai * 4 + m];
;                 const float c1 = -1.4426950408889634f * r, r2 = r * r;
;                 const f32x4 ga = acc[ai][0][m][0], gb = acc[ai][0][m][1];
;                 const f32x4 ta = ga * c1, tb = gb * c1;
;                 f32x4 ea, eb;
; #pragma unroll
;                 for (int j = 0; j < 4; ++j) { ea[j] = fast_exp2(ta[j]); eb[j] = fast_exp2(tb[j]); }
;                 const f32x4 da = ea + 1.f, db = eb + 1.f;
;                 f32x4 qa, qb;
; #pragma unroll
;                 for (int j = 0; j < 4; ++j) { qa[j] = fast_rcp(da[j]); qb[j] = fast_rcp(db[j]); }
;                 const f32x4 oa = ((ga * acc[ai][1][m][0]) * r2) * qa, ob = ((gb * acc[ai][1][m][1]) * r2) * qb;
;                 u32x4 w;
;                 w.x = pk_bf16(oa[0], oa[1]); w.y = pk_bf16(oa[2], oa[3]); w.z = pk_bf16(ob[0], ob[1]); w.w = pk_bf16(ob[2], ob[3]);
;                 if (ai == 0 && m == 0) rstd_finish(raw0, raw1, rn0, rn1);
;                 *(u32x4*)(O + (size_t)row * FF + col0) = w;
	v_mul_f32_e32 v228, 0xbfb8aa3b, v165
	v_pk_mul_f32 v[78:79], v[70:71], v[78:79]
	v_pk_mul_f32 v[80:81], v[72:73], v[80:81]
	v_pk_mul_f32 v[74:75], v[62:63], v[74:75]
	v_pk_mul_f32 v[76:77], v[64:65], v[76:77]
	v_pk_mul_f32 v[70:71], v[70:71], v[228:229] op_sel_hi:[1,0]
	v_pk_mul_f32 v[72:73], v[72:73], v[228:229] op_sel_hi:[1,0]
	v_pk_mul_f32 v[62:63], v[62:63], v[228:229] op_sel_hi:[1,0]
	v_pk_mul_f32 v[64:65], v[64:65], v[228:229] op_sel_hi:[1,0]
	v_exp_f32_e32 v70, v70
	v_exp_f32_e32 v71, v71
	v_exp_f32_e32 v72, v72
	v_exp_f32_e32 v73, v73
	v_exp_f32_e32 v62, v62
	v_exp_f32_e32 v63, v63
	v_exp_f32_e32 v64, v64
	v_exp_f32_e32 v65, v65
	v_pk_fma_f32 v[70:71], v[70:71], v[206:207], v[206:207] op_sel_hi:[1,0,0]
	v_pk_fma_f32 v[72:73], v[72:73], v[206:207], v[206:207] op_sel_hi:[1,0,0]
	v_pk_fma_f32 v[62:63], v[62:63], v[206:207], v[206:207] op_sel_hi:[1,0,0]
	v_pk_fma_f32 v[64:65], v[64:65], v[206:207], v[206:207] op_sel_hi:[1,0,0]
	v_rcp_f32_e32 v70, v70
	v_rcp_f32_e32 v71, v71
	v_rcp_f32_e32 v72, v72
	v_rcp_f32_e32 v73, v73
	v_rcp_f32_e32 v62, v62
	v_rcp_f32_e32 v63, v63
	v_rcp_f32_e32 v64, v64
	v_rcp_f32_e32 v65, v65
	v_pk_mul_f32 v[78:79], v[78:79], v[70:71]
	v_pk_mul_f32 v[80:81], v[80:81], v[72:73]
	v_pk_mul_f32 v[74:75], v[74:75], v[62:63]
	v_pk_mul_f32 v[76:77], v[76:77], v[64:65]
	v_cvt_pk_bf16_f32 v70, v78, v79
	v_cvt_pk_bf16_f32 v71, v80, v81
	v_cvt_pk_bf16_f32 v72, v74, v75
	v_cvt_pk_bf16_f32 v73, v76, v77
	v_add_u32_e32 v170, 0x42000, v161
	global_store_dwordx4 v170, v[70:73], s[24:25]
	s_waitcnt lgkmcnt(6)
	v_mul_f32_e32 v228, 0xbfb8aa3b, v166
	v_pk_mul_f32 v[66:67], v[54:55], v[66:67]
	v_pk_mul_f32 v[68:69], v[56:57], v[68:69]
	v_pk_mul_f32 v[58:59], v[50:51], v[58:59]
	v_pk_mul_f32 v[60:61], v[52:53], v[60:61]
	v_pk_mul_f32 v[54:55], v[54:55], v[228:229] op_sel_hi:[1,0]
	v_pk_mul_f32 v[56:57], v[56:57], v[228:229] op_sel_hi:[1,0]
	v_pk_mul_f32 v[50:51], v[50:51], v[228:229] op_sel_hi:[1,0]
	v_pk_mul_f32 v[52:53], v[52:53], v[228:229] op_sel_hi:[1,0]
	v_exp_f32_e32 v54, v54
	v_exp_f32_e32 v55, v55
	v_exp_f32_e32 v56, v56
	v_exp_f32_e32 v57, v57
	v_exp_f32_e32 v50, v50
	v_exp_f32_e32 v51, v51
	v_exp_f32_e32 v52, v52
	v_exp_f32_e32 v53, v53
	v_pk_fma_f32 v[54:55], v[54:55], v[220:221], v[220:221] op_sel_hi:[1,0,0]
	v_pk_fma_f32 v[56:57], v[56:57], v[220:221], v[220:221] op_sel_hi:[1,0,0]
	v_pk_fma_f32 v[50:51], v[50:51], v[220:221], v[220:221] op_sel_hi:[1,0,0]
	v_pk_fma_f32 v[52:53], v[52:53], v[220:221], v[220:221] op_sel_hi:[1,0,0]
	v_rcp_f32_e32 v54, v54
	v_rcp_f32_e32 v55, v55
	v_rcp_f32_e32 v56, v56
	v_rcp_f32_e32 v57, v57
	v_rcp_f32_e32 v50, v50
	v_rcp_f32_e32 v51, v51
	v_rcp_f32_e32 v52, v52
	v_rcp_f32_e32 v53, v53
	v_pk_mul_f32 v[66:67], v[66:67], v[54:55]
	v_pk_mul_f32 v[68:69], v[68:69], v[56:57]
	v_pk_mul_f32 v[58:59], v[58:59], v[50:51]
	v_pk_mul_f32 v[60:61], v[60:61], v[52:53]
	v_cvt_pk_bf16_f32 v54, v66, v67
	v_cvt_pk_bf16_f32 v55, v68, v69
	v_cvt_pk_bf16_f32 v56, v58, v59
	v_cvt_pk_bf16_f32 v57, v60, v61
	v_add_u32_e32 v170, 0xb0000, v161
	global_store_dwordx4 v170, v[54:57], s[24:25]
	s_waitcnt lgkmcnt(4)
	v_mul_f32_e32 v228, 0xbfb8aa3b, v167
	v_pk_mul_f32 v[46:47], v[38:39], v[46:47]
	v_pk_mul_f32 v[48:49], v[40:41], v[48:49]
	v_pk_mul_f32 v[42:43], v[34:35], v[42:43]
	v_pk_mul_f32 v[44:45], v[36:37], v[44:45]
	v_pk_mul_f32 v[38:39], v[38:39], v[228:229] op_sel_hi:[1,0]
	v_pk_mul_f32 v[40:41], v[40:41], v[228:229] op_sel_hi:[1,0]
	v_pk_mul_f32 v[34:35], v[34:35], v[228:229] op_sel_hi:[1,0]
	v_pk_mul_f32 v[36:37], v[36:37], v[228:229] op_sel_hi:[1,0]
	v_exp_f32_e32 v38, v38
	v_exp_f32_e32 v39, v39
	v_exp_f32_e32 v40, v40
	v_exp_f32_e32 v41, v41
	v_exp_f32_e32 v34, v34
	v_exp_f32_e32 v35, v35
	v_exp_f32_e32 v36, v36
	v_exp_f32_e32 v37, v37
	v_pk_fma_f32 v[38:39], v[38:39], v[222:223], v[222:223] op_sel_hi:[1,0,0]
	v_pk_fma_f32 v[40:41], v[40:41], v[222:223], v[222:223] op_sel_hi:[1,0,0]
	v_pk_fma_f32 v[34:35], v[34:35], v[222:223], v[222:223] op_sel_hi:[1,0,0]
	v_pk_fma_f32 v[36:37], v[36:37], v[222:223], v[222:223] op_sel_hi:[1,0,0]
	v_rcp_f32_e32 v38, v38
	v_rcp_f32_e32 v39, v39
	v_rcp_f32_e32 v40, v40
	v_rcp_f32_e32 v41, v41
	v_rcp_f32_e32 v34, v34
	v_rcp_f32_e32 v35, v35
	v_rcp_f32_e32 v36, v36
	v_rcp_f32_e32 v37, v37
	v_pk_mul_f32 v[46:47], v[46:47], v[38:39]
	v_pk_mul_f32 v[48:49], v[48:49], v[40:41]
	v_pk_mul_f32 v[42:43], v[42:43], v[34:35]
	v_pk_mul_f32 v[44:45], v[44:45], v[36:37]
	v_cvt_pk_bf16_f32 v38, v46, v47
	v_cvt_pk_bf16_f32 v39, v48, v49
	v_cvt_pk_bf16_f32 v40, v42, v43
	v_cvt_pk_bf16_f32 v41, v44, v45
	v_add_u32_e32 v170, 0xc6000, v161
	global_store_dwordx4 v170, v[38:41], s[24:25]
	s_waitcnt lgkmcnt(2)
; __device__ __forceinline__ unsigned pk_bf16(float lo, float hi) { f32x2 v = {lo, hi}; bf16x2_t b = __builtin_convertvector(v, bf16x2_t); return __builtin_bit_cast(unsigned, b); }
; __device__ __forceinline__ float fast_exp2(float x) { return __builtin_amdgcn_exp2f(x); }
; __device__ __forceinline__ float fast_rcp(float x) { return __builtin_amdgcn_rcpf(x); }
; __device__ __forceinline__ void rstd_finish(const f32x4& raw0, const f32x4& raw1, float& rn0, float& rn1) {
;     rn0 = rsqrtf(((raw0.x + raw0.y) + (raw0.z + raw0.w)) * (1.f / DM) + EPS); rn1 = rsqrtf(((raw1.x + raw1.y) + (raw1.z + raw1.w)) * (1.f / DM) + EPS);
;     asm volatile("" :: "v"(rn0), "v"(rn1) : "memory");
;     __device__ __forceinline__ void operator()(const f32x4 (&acc)[2][2][4][2], const Unit& u, int wr, int wc, int fr, int fq, float rp0, float rp1, const f32x4& raw0, const f32x4& raw1, float& rn0, float& rn1) const {
;     ...
;                 const int row = row0 + ai * HALF + m * 16; const float r = rs[ai * 4 + m];
;                 const float c1 = -1.4426950408889634f * r, r2 = r * r;
;                 const f32x4 ga = acc[ai][0][m][0], gb = acc[ai][0][m][1];
;                 const f32x4 ta = ga * c1, tb = gb * c1;
;                 f32x4 ea, eb;
; #pragma unroll
;                 for (int j = 0; j < 4; ++j) { ea[j] = fast_exp2(ta[j]); eb[j] = fast_exp2(tb[j]); }
;                 const f32x4 da = ea + 1.f, db = eb + 1.f;
;                 f32x4 qa, qb;
; #pragma unroll
;                 for (int j = 0; j < 4; ++j) { qa[j] = fast_rcp(da[j]); qb[j] = fast_rcp(db[j]); }
;                 const f32x4 oa = ((ga * acc[ai][1][m][0]) * r2) * qa, ob = ((gb * acc[ai][1][m][1]) * r2) * qb;
;                 u32x4 w;
;                 w.x = pk_bf16(oa[0], oa[1]); w.y = pk_bf16(oa[2], oa[3]); w.z = pk_bf16(ob[0], ob[1]); w.w = pk_bf16(ob[2], ob[3]);
;                 if (ai == 0 && m == 0) rstd_finish(raw0, raw1, rn0, rn1);
;                 *(u32x4*)(O + (size_t)row * FF + col0) = w;
	v_mul_f32_e32 v228, 0xbfb8aa3b, v168
	v_pk_mul_f32 v[30:31], v[22:23], v[30:31]
	v_pk_mul_f32 v[32:33], v[24:25], v[32:33]
	v_pk_mul_f32 v[26:27], v[18:19], v[26:27]
	v_pk_mul_f32 v[28:29], v[20:21], v[28:29]
	v_pk_mul_f32 v[22:23], v[22:23], v[228:229] op_sel_hi:[1,0]
	v_pk_mul_f32 v[24:25], v[24:25], v[228:229] op_sel_hi:[1,0]
	v_pk_mul_f32 v[18:19], v[18:19], v[228:229] op_sel_hi:[1,0]
	v_pk_mul_f32 v[20:21], v[20:21], v[228:229] op_sel_hi:[1,0]
	v_exp_f32_e32 v22, v22
	v_exp_f32_e32 v23, v23
	v_exp_f32_e32 v24, v24
	v_exp_f32_e32 v25, v25
	v_exp_f32_e32 v18, v18
	v_exp_f32_e32 v19, v19
	v_exp_f32_e32 v20, v20
	v_exp_f32_e32 v21, v21
	v_pk_fma_f32 v[22:23], v[22:23], v[224:225], v[224:225] op_sel_hi:[1,0,0]
	v_pk_fma_f32 v[24:25], v[24:25], v[224:225], v[224:225] op_sel_hi:[1,0,0]
	v_pk_fma_f32 v[18:19], v[18:19], v[224:225], v[224:225] op_sel_hi:[1,0,0]
	v_pk_fma_f32 v[20:21], v[20:21], v[224:225], v[224:225] op_sel_hi:[1,0,0]
	v_rcp_f32_e32 v22, v22
	v_rcp_f32_e32 v23, v23
	v_rcp_f32_e32 v24, v24
	v_rcp_f32_e32 v25, v25
	v_rcp_f32_e32 v18, v18
	v_rcp_f32_e32 v19, v19
	v_rcp_f32_e32 v20, v20
	v_rcp_f32_e32 v21, v21
	v_pk_mul_f32 v[30:31], v[30:31], v[22:23]
	v_pk_mul_f32 v[32:33], v[32:33], v[24:25]
	v_pk_mul_f32 v[26:27], v[26:27], v[18:19]
	v_pk_mul_f32 v[28:29], v[28:29], v[20:21]
	v_cvt_pk_bf16_f32 v22, v30, v31
	v_cvt_pk_bf16_f32 v23, v32, v33
	v_cvt_pk_bf16_f32 v24, v26, v27
	v_cvt_pk_bf16_f32 v25, v28, v29
	v_add_u32_e32 v170, 0xdc000, v161
	global_store_dwordx4 v170, v[22:25], s[24:25]
	s_waitcnt lgkmcnt(0)
	v_mul_f32_e32 v228, 0xbfb8aa3b, v169
	v_pk_mul_f32 v[14:15], v[6:7], v[14:15]
	v_pk_mul_f32 v[16:17], v[8:9], v[16:17]
	v_pk_mul_f32 v[10:11], v[2:3], v[10:11]
	v_pk_mul_f32 v[12:13], v[4:5], v[12:13]
	v_pk_mul_f32 v[6:7], v[6:7], v[228:229] op_sel_hi:[1,0]
	v_pk_mul_f32 v[8:9], v[8:9], v[228:229] op_sel_hi:[1,0]
	v_pk_mul_f32 v[2:3], v[2:3], v[228:229] op_sel_hi:[1,0]
	v_pk_mul_f32 v[4:5], v[4:5], v[228:229] op_sel_hi:[1,0]
	v_exp_f32_e32 v6, v6
	v_exp_f32_e32 v7, v7
	v_exp_f32_e32 v8, v8
	v_exp_f32_e32 v9, v9
	v_exp_f32_e32 v2, v2
	v_exp_f32_e32 v3, v3
	v_exp_f32_e32 v4, v4
	v_exp_f32_e32 v5, v5
	v_pk_fma_f32 v[6:7], v[6:7], v[226:227], v[226:227] op_sel_hi:[1,0,0]
	v_pk_fma_f32 v[8:9], v[8:9], v[226:227], v[226:227] op_sel_hi:[1,0,0]
	v_pk_fma_f32 v[2:3], v[2:3], v[226:227], v[226:227] op_sel_hi:[1,0,0]
	v_pk_fma_f32 v[4:5], v[4:5], v[226:227], v[226:227] op_sel_hi:[1,0,0]
	v_rcp_f32_e32 v6, v6
	v_rcp_f32_e32 v7, v7
	v_rcp_f32_e32 v8, v8
	v_rcp_f32_e32 v9, v9
	v_rcp_f32_e32 v2, v2
	v_rcp_f32_e32 v3, v3
	v_rcp_f32_e32 v4, v4
	v_rcp_f32_e32 v5, v5
	v_pk_mul_f32 v[14:15], v[14:15], v[6:7]
	v_pk_mul_f32 v[16:17], v[16:17], v[8:9]
	v_pk_mul_f32 v[10:11], v[10:11], v[2:3]
	v_pk_mul_f32 v[12:13], v[12:13], v[4:5]
	v_cvt_pk_bf16_f32 v6, v14, v15
	v_cvt_pk_bf16_f32 v7, v16, v17
	v_cvt_pk_bf16_f32 v8, v10, v11
	v_cvt_pk_bf16_f32 v9, v12, v13
	v_add_u32_e32 v170, 0xf2000, v161
	global_store_dwordx4 v170, v[6:9], s[24:25]
	s_waitcnt vmcnt(8)
	v_mov_b32_e32 v122, v135
	v_mov_b32_e32 v123, v136
	v_mov_b32_e32 v135, v137
	v_mov_b32_e32 v124, v131
	v_mov_b32_e32 v125, v132
	v_mov_b32_e32 v131, v133
	v_pk_add_f32 v[122:123], v[122:123], v[134:135]
	v_pk_add_f32 v[124:125], v[124:125], v[130:131]
	v_mov_b32_e32 v126, v124
	v_mov_b32_e32 v127, v122
	v_mov_b32_e32 v122, v125
	v_pk_add_f32 v[122:123], v[126:127], v[122:123]
	v_pk_fma_f32 v[122:123], v[122:123], s[84:85], v[182:183] op_sel_hi:[1,0,0]
	v_mov_b32_e32 v252, v122
	v_mov_b32_e32 v253, v123
	v_mul_f32_e32 v119, 0x4b800000, v123
	v_mul_f32_e32 v118, 0x4b800000, v122
	v_cmp_gt_f32_e64 s[100:101], s89, v123
	v_cmp_gt_f32_e64 s[6:7], s89, v122
	s_nop 1
	v_cndmask_b32_e64 v119, v123, v119, s[100:101]
	v_cndmask_b32_e64 v118, v122, v118, s[6:7]
	v_rsq_f32_e32 v123, v119
	v_rsq_f32_e32 v122, v118
	s_nop 0
	v_pk_mul_f32 v[120:121], v[122:123], s[78:79] op_sel_hi:[1,0]
	v_cndmask_b32_e64 v145, v123, v121, s[100:101]
	v_cndmask_b32_e64 v144, v122, v120, s[6:7]
	s_cbranch_vccnz .LBB0_315
	s_andn2_b64 vcc, exec, s[2:3]
	s_cbranch_vccnz .LBB0_314
	s_barrier
	s_branch .LBB0_314
